# SwiGLU epilogue: issue the 1/rms load burst before the epilogue alignment barrier so it overlaps the barrier wait
# baseline (speedup 1.0000x reference)
; #define PG8_STAGE(bufoff, gbase, voff) do { _Pragma("unroll") for (int _i = 0; _i < 2; ++_i) \
;         __builtin_amdgcn_global_load_lds((const unsigned*)((const char*)(gbase) + (voff)[_i]), (LAS unsigned*)(lds + (bufoff) + ldsw + _i * 8192), 16, 0, 0); } while (0)
; #define PG8_LDA(dst, b, h) do { _Pragma("unroll") for (int m = 0; m < 4; ++m) _Pragma("unroll") for (int k = 0; k < 2; ++k) dst[m][k] = *(const LAS bf16x8*)(lds + PG8_SA(b, h) + aoff + m * 2048 + k * 1024); } while (0)
; #define PG8_LDB(dst, b, h) do { _Pragma("unroll") for (int n = 0; n < 2; ++n) _Pragma("unroll") for (int k = 0; k < 2; ++k) dst[n][k] = *(const LAS bf16x8*)(lds + PG8_SB(b, h) + boff + n * 2048 + k * 1024); } while (0)
; #define PG8_MMA(ai, bj, At, Bt) do { __builtin_amdgcn_s_setprio(1); _Pragma("unroll") for (int m = 0; m < 4; ++m) _Pragma("unroll") for (int n = 0; n < 2; ++n) _Pragma("unroll") for (int k = 0; k < 2; ++k) \
;         acc[ai][bj][m][n] = __builtin_amdgcn_mfma_f32_16x16x32_bf16(Bt[n][k], At[m][k], acc[ai][bj][m][n], 0, 0, 0); __builtin_amdgcn_s_setprio(0); } while (0)
; #define PG8_WAIT_V(n) asm volatile("s_waitcnt vmcnt(" #n ")" ::: "memory")
; #define PG8_WAIT_L(n) asm volatile("s_waitcnt lgkmcnt(" #n ")" ::: "memory")
; #define PG8_BAR __builtin_amdgcn_s_barrier()
; #define PG8_SCHED __builtin_amdgcn_sched_barrier(0)
; template <class Epi>
; DI void gemm_phase(LAS unsigned char* lds, const Gemm g, const StaticOrder& S, const Epi& E) {
;     ...
;             PG8_LDB(B0, 0, 0); PG8_LDB(B1, 0, 1); PG8_SCHED; PG8_LDA(At, 0, 0); PG8_STAGE(PG8_SA(1, 1), a1 + hstep, voffA);
;             PG8_WAIT_V(8); PG8_WAIT_L(0); PG8_BAR; PG8_MMA(0, 0, At, B0); PG8_MMA(0, 1, At, B1); PG8_BAR; PG8_SCHED;
;             PG8_LDA(At, 0, 1); PG8_STAGE(PG8_SB(0, 0), b2, voffB); PG8_STAGE(PG8_SB(0, 1), b2 + hstep, voffB); PG8_STAGE(PG8_SA(0, 0), a2, voffA);
;             PG8_WAIT_V(8); PG8_WAIT_L(0); PG8_BAR; PG8_MMA(1, 0, At, B0); PG8_MMA(1, 1, At, B1); PG8_BAR; PG8_SCHED;
;             PG8_LDB(B0, 1, 0); PG8_LDB(B1, 1, 1); PG8_SCHED; PG8_LDA(At, 1, 0); PG8_STAGE(PG8_SA(0, 1), a2 + hstep, voffA);
;             PG8_WAIT_V(8); PG8_WAIT_L(0); PG8_BAR; PG8_MMA(0, 0, At, B0); PG8_MMA(0, 1, At, B1); PG8_BAR; PG8_SCHED;
.LBB0_701:
	s_add_u32 s16, s18, 0xfff80080
	s_addc_u32 s17, s19, -1
	s_add_i32 s46, 0, 0x10000
	s_cmp_eq_u32 s43, 28
	s_cselect_b32 s21, s11, s17
	s_cselect_b32 s20, s39, s16
	v_add_u32_e32 v160, s46, v162
	s_cselect_b32 s17, s9, s42
	s_cselect_b32 s16, s40, s41
	s_add_i32 s48, 0, 0x14000
	ds_read_b128 v[156:159], v160
	ds_read_b128 v[174:177], v160 offset:1024
	ds_read_b128 v[178:181], v160 offset:2048
	ds_read_b128 v[182:185], v160 offset:3072
	v_add_u32_e32 v160, s48, v162
	ds_read_b128 v[186:189], v160
	ds_read_b128 v[190:193], v160 offset:1024
	ds_read_b128 v[194:197], v160 offset:2048
	ds_read_b128 v[198:201], v160 offset:3072
	v_lshl_add_u64 v[160:161], s[18:19], 0, v[152:153]
	s_add_i32 m0, s27, 0xc000
	ds_read_b128 v[202:205], v165
	ds_read_b128 v[206:209], v165 offset:1024
	ds_read_b128 v[210:213], v165 offset:2048
	ds_read_b128 v[226:229], v165 offset:3072
	ds_read_b128 v[230:233], v165 offset:4096
	ds_read_b128 v[234:237], v165 offset:5120
	ds_read_b128 v[238:241], v165 offset:6144
	ds_read_b128 v[242:245], v165 offset:7168
	global_load_lds_dwordx4 v[160:161], off
	v_lshl_add_u64 v[160:161], s[18:19], 0, v[154:155]
	s_add_i32 m0, s27, 0xe000
	s_nop 0
	global_load_lds_dwordx4 v[160:161], off
	s_waitcnt vmcnt(8)
	s_waitcnt lgkmcnt(0)
	s_barrier
	s_setprio 1
	s_waitcnt lgkmcnt(0)
	v_mfma_f32_16x16x32_bf16 v[134:137], v[156:159], v[202:205], v[134:137]
	v_mfma_f32_16x16x32_bf16 v[130:133], v[178:181], v[202:205], v[130:133]
	v_mfma_f32_16x16x32_bf16 v[118:121], v[156:159], v[210:213], v[118:121]
	v_mfma_f32_16x16x32_bf16 v[114:117], v[178:181], v[210:213], v[114:117]
	v_mfma_f32_16x16x32_bf16 v[102:105], v[156:159], v[230:233], v[102:105]
	v_mfma_f32_16x16x32_bf16 v[98:101], v[178:181], v[230:233], v[98:101]
	v_mfma_f32_16x16x32_bf16 v[68:71], v[156:159], v[238:241], v[68:71]
	v_mfma_f32_16x16x32_bf16 v[64:67], v[178:181], v[238:241], v[64:67]
	v_mfma_f32_16x16x32_bf16 v[134:137], v[174:177], v[206:209], v[134:137]
	v_mfma_f32_16x16x32_bf16 v[130:133], v[182:185], v[206:209], v[130:133]
	v_mfma_f32_16x16x32_bf16 v[118:121], v[174:177], v[226:229], v[118:121]
	v_mfma_f32_16x16x32_bf16 v[114:117], v[182:185], v[226:229], v[114:117]
	v_mfma_f32_16x16x32_bf16 v[102:105], v[174:177], v[234:237], v[102:105]
	v_mfma_f32_16x16x32_bf16 v[98:101], v[182:185], v[234:237], v[98:101]
	v_mfma_f32_16x16x32_bf16 v[68:71], v[174:177], v[242:245], v[68:71]
	v_mfma_f32_16x16x32_bf16 v[64:67], v[182:185], v[242:245], v[64:67]
	s_setprio 0
	s_setprio 1
	v_mfma_f32_16x16x32_bf16 v[142:145], v[186:189], v[202:205], v[142:145]
	v_mfma_f32_16x16x32_bf16 v[138:141], v[194:197], v[202:205], v[138:141]
	v_mfma_f32_16x16x32_bf16 v[126:129], v[186:189], v[210:213], v[126:129]
	v_mfma_f32_16x16x32_bf16 v[122:125], v[194:197], v[210:213], v[122:125]
	v_mfma_f32_16x16x32_bf16 v[110:113], v[186:189], v[230:233], v[110:113]
	v_mfma_f32_16x16x32_bf16 v[106:109], v[194:197], v[230:233], v[106:109]
	v_mfma_f32_16x16x32_bf16 v[76:79], v[186:189], v[238:241], v[76:79]
	v_mfma_f32_16x16x32_bf16 v[72:75], v[194:197], v[238:241], v[72:75]
	v_mfma_f32_16x16x32_bf16 v[142:145], v[190:193], v[206:209], v[142:145]
	v_mfma_f32_16x16x32_bf16 v[138:141], v[198:201], v[206:209], v[138:141]
	v_mfma_f32_16x16x32_bf16 v[126:129], v[190:193], v[226:229], v[126:129]
	v_mfma_f32_16x16x32_bf16 v[122:125], v[198:201], v[226:229], v[122:125]
	v_mfma_f32_16x16x32_bf16 v[110:113], v[190:193], v[234:237], v[110:113]
	v_mfma_f32_16x16x32_bf16 v[106:109], v[198:201], v[234:237], v[106:109]
	v_mfma_f32_16x16x32_bf16 v[76:79], v[190:193], v[242:245], v[76:79]
	v_mfma_f32_16x16x32_bf16 v[72:75], v[198:201], v[242:245], v[72:75]
	s_setprio 0
	s_barrier
	s_add_i32 s46, s46, s26
	v_lshl_add_u64 v[160:161], s[16:17], 0, v[80:81]
	s_mov_b32 m0, s46
	ds_read_b128 v[202:205], v165 offset:16384
	ds_read_b128 v[206:209], v165 offset:17408
	ds_read_b128 v[210:213], v165 offset:18432
	ds_read_b128 v[226:229], v165 offset:19456
	ds_read_b128 v[230:233], v165 offset:20480
	ds_read_b128 v[234:237], v165 offset:21504
	ds_read_b128 v[238:241], v165 offset:22528
	ds_read_b128 v[242:245], v165 offset:23552
	global_load_lds_dwordx4 v[160:161], off
	s_add_i32 m0, s46, 0x2000
	s_add_u32 s46, s16, 0x80000
	v_lshl_add_u64 v[214:215], s[16:17], 0, v[146:147]
	s_addc_u32 s47, s17, 0
	s_add_i32 s48, s48, s26
	global_load_lds_dwordx4 v[214:215], off
	v_lshl_add_u64 v[216:217], s[46:47], 0, v[80:81]
	s_mov_b32 m0, s48
	v_lshl_add_u64 v[218:219], s[20:21], 0, v[148:149]
	global_load_lds_dwordx4 v[216:217], off
	v_lshl_add_u64 v[216:217], s[46:47], 0, v[146:147]
	s_add_i32 m0, s48, 0x2000
	s_nop 0
	global_load_lds_dwordx4 v[216:217], off
	v_lshl_add_u64 v[216:217], s[20:21], 0, v[150:151]
	s_mov_b32 m0, s27
	s_nop 0
	global_load_lds_dwordx4 v[216:217], off
	s_mov_b32 m0, s28
	s_nop 0
	global_load_lds_dwordx4 v[218:219], off
	s_waitcnt vmcnt(8)
	s_waitcnt lgkmcnt(0)
	s_barrier
; #define PG8_STAGE(bufoff, gbase, voff) do { _Pragma("unroll") for (int _i = 0; _i < 2; ++_i) \
;         __builtin_amdgcn_global_load_lds((const unsigned*)((const char*)(gbase) + (voff)[_i]), (LAS unsigned*)(lds + (bufoff) + ldsw + _i * 8192), 16, 0, 0); } while (0)
; #define PG8_LDA(dst, b, h) do { _Pragma("unroll") for (int m = 0; m < 4; ++m) _Pragma("unroll") for (int k = 0; k < 2; ++k) dst[m][k] = *(const LAS bf16x8*)(lds + PG8_SA(b, h) + aoff + m * 2048 + k * 1024); } while (0)
; #define PG8_MMA(ai, bj, At, Bt) do { __builtin_amdgcn_s_setprio(1); _Pragma("unroll") for (int m = 0; m < 4; ++m) _Pragma("unroll") for (int n = 0; n < 2; ++n) _Pragma("unroll") for (int k = 0; k < 2; ++k) \
;         acc[ai][bj][m][n] = __builtin_amdgcn_mfma_f32_16x16x32_bf16(Bt[n][k], At[m][k], acc[ai][bj][m][n], 0, 0, 0); __builtin_amdgcn_s_setprio(0); } while (0)
; #define PG8_WAIT_V(n) asm volatile("s_waitcnt vmcnt(" #n ")" ::: "memory")
; #define PG8_WAIT_L(n) asm volatile("s_waitcnt lgkmcnt(" #n ")" ::: "memory")
; #define PG8_BAR __builtin_amdgcn_s_barrier()
; #define PG8_SCHED __builtin_amdgcn_sched_barrier(0)
; template <class Epi>
; DI void gemm_phase(LAS unsigned char* lds, const Gemm g, const StaticOrder& S, const Epi& E) {
;     ...
;             PG8_WAIT_V(8); PG8_WAIT_L(0); PG8_BAR; PG8_MMA(0, 0, At, B0); PG8_MMA(0, 1, At, B1); PG8_BAR; PG8_SCHED;
;             PG8_LDA(At, 1, 1); PG8_STAGE(PG8_SB(1, 0), b3, voffB); PG8_STAGE(PG8_SB(1, 1), b3 + hstep, voffB); PG8_STAGE(PG8_SA(1, 0), a3, voffA);
;             PG8_WAIT_V(8); PG8_WAIT_L(0); PG8_BAR; PG8_MMA(1, 0, At, B0); PG8_MMA(1, 1, At, B1); PG8_BAR; PG8_SCHED;
	s_setprio 1
	s_waitcnt lgkmcnt(0)
	v_mfma_f32_16x16x32_bf16 v[52:55], v[156:159], v[202:205], v[52:55]
	v_mfma_f32_16x16x32_bf16 v[48:51], v[178:181], v[202:205], v[48:51]
	v_mfma_f32_16x16x32_bf16 v[36:39], v[156:159], v[210:213], v[36:39]
	v_mfma_f32_16x16x32_bf16 v[32:35], v[178:181], v[210:213], v[32:35]
	v_mfma_f32_16x16x32_bf16 v[20:23], v[156:159], v[230:233], v[20:23]
	v_mfma_f32_16x16x32_bf16 v[16:19], v[178:181], v[230:233], v[16:19]
	v_mfma_f32_16x16x32_bf16 v[4:7], v[156:159], v[238:241], v[4:7]
	v_mfma_f32_16x16x32_bf16 v[0:3], v[178:181], v[238:241], v[0:3]
	v_mfma_f32_16x16x32_bf16 v[52:55], v[174:177], v[206:209], v[52:55]
	v_mfma_f32_16x16x32_bf16 v[48:51], v[182:185], v[206:209], v[48:51]
	v_mfma_f32_16x16x32_bf16 v[36:39], v[174:177], v[226:229], v[36:39]
	v_mfma_f32_16x16x32_bf16 v[32:35], v[182:185], v[226:229], v[32:35]
	v_mfma_f32_16x16x32_bf16 v[20:23], v[174:177], v[234:237], v[20:23]
	v_mfma_f32_16x16x32_bf16 v[16:19], v[182:185], v[234:237], v[16:19]
	v_mfma_f32_16x16x32_bf16 v[4:7], v[174:177], v[242:245], v[4:7]
	v_mfma_f32_16x16x32_bf16 v[0:3], v[182:185], v[242:245], v[0:3]
	s_setprio 0
	s_setprio 1
	v_mfma_f32_16x16x32_bf16 v[60:63], v[186:189], v[202:205], v[60:63]
	v_mfma_f32_16x16x32_bf16 v[56:59], v[194:197], v[202:205], v[56:59]
	v_mfma_f32_16x16x32_bf16 v[44:47], v[186:189], v[210:213], v[44:47]
	v_mfma_f32_16x16x32_bf16 v[40:43], v[194:197], v[210:213], v[40:43]
	v_mfma_f32_16x16x32_bf16 v[28:31], v[186:189], v[230:233], v[28:31]
	v_mfma_f32_16x16x32_bf16 v[24:27], v[194:197], v[230:233], v[24:27]
	v_mfma_f32_16x16x32_bf16 v[12:15], v[186:189], v[238:241], v[12:15]
	v_mfma_f32_16x16x32_bf16 v[8:11], v[194:197], v[238:241], v[8:11]
	v_mfma_f32_16x16x32_bf16 v[60:63], v[190:193], v[206:209], v[60:63]
	v_mfma_f32_16x16x32_bf16 v[56:59], v[198:201], v[206:209], v[56:59]
	v_mfma_f32_16x16x32_bf16 v[44:47], v[190:193], v[226:229], v[44:47]
	v_mfma_f32_16x16x32_bf16 v[40:43], v[198:201], v[226:229], v[40:43]
	v_mfma_f32_16x16x32_bf16 v[28:31], v[190:193], v[234:237], v[28:31]
	v_mfma_f32_16x16x32_bf16 v[24:27], v[198:201], v[234:237], v[24:27]
	v_mfma_f32_16x16x32_bf16 v[12:15], v[190:193], v[242:245], v[12:15]
	v_mfma_f32_16x16x32_bf16 v[8:11], v[198:201], v[242:245], v[8:11]
	s_setprio 0
	s_barrier
	s_add_i32 s46, 0, 0x18000
	v_add_u32_e32 v169, s46, v162
	s_add_i32 s47, 0, 0x1c000
	ds_read_b128 v[156:159], v169
	ds_read_b128 v[174:177], v169 offset:1024
	ds_read_b128 v[178:181], v169 offset:2048
	ds_read_b128 v[182:185], v169 offset:3072
	v_add_u32_e32 v169, s47, v162
	ds_read_b128 v[186:189], v169
	ds_read_b128 v[190:193], v169 offset:1024
	ds_read_b128 v[194:197], v169 offset:2048
	ds_read_b128 v[198:201], v169 offset:3072
	s_add_u32 s20, s20, 0x80000
	s_addc_u32 s21, s21, 0
	s_mov_b32 m0, s29
	v_lshl_add_u64 v[246:247], s[20:21], 0, v[150:151]
	ds_read_b128 v[202:205], v165 offset:32768
	ds_read_b128 v[206:209], v165 offset:33792
	ds_read_b128 v[210:213], v165 offset:34816
	ds_read_b128 v[226:229], v165 offset:35840
	ds_read_b128 v[230:233], v165 offset:36864
	ds_read_b128 v[234:237], v165 offset:37888
	ds_read_b128 v[238:241], v165 offset:38912
	ds_read_b128 v[242:245], v165 offset:39936
	global_load_lds_dwordx4 v[246:247], off
	v_lshl_add_u64 v[246:247], s[20:21], 0, v[148:149]
	s_mov_b32 m0, s30
	s_nop 0
	global_load_lds_dwordx4 v[246:247], off
	s_waitcnt vmcnt(8)
	s_waitcnt lgkmcnt(0)
	s_barrier
	s_setprio 1
	s_waitcnt lgkmcnt(0)
	v_mfma_f32_16x16x32_bf16 v[134:137], v[156:159], v[202:205], v[134:137]
	v_mfma_f32_16x16x32_bf16 v[130:133], v[178:181], v[202:205], v[130:133]
	v_mfma_f32_16x16x32_bf16 v[118:121], v[156:159], v[210:213], v[118:121]
	v_mfma_f32_16x16x32_bf16 v[114:117], v[178:181], v[210:213], v[114:117]
	v_mfma_f32_16x16x32_bf16 v[102:105], v[156:159], v[230:233], v[102:105]
	v_mfma_f32_16x16x32_bf16 v[98:101], v[178:181], v[230:233], v[98:101]
	v_mfma_f32_16x16x32_bf16 v[68:71], v[156:159], v[238:241], v[68:71]
	v_mfma_f32_16x16x32_bf16 v[64:67], v[178:181], v[238:241], v[64:67]
	v_mfma_f32_16x16x32_bf16 v[134:137], v[174:177], v[206:209], v[134:137]
	v_mfma_f32_16x16x32_bf16 v[130:133], v[182:185], v[206:209], v[130:133]
	v_mfma_f32_16x16x32_bf16 v[118:121], v[174:177], v[226:229], v[118:121]
	v_mfma_f32_16x16x32_bf16 v[114:117], v[182:185], v[226:229], v[114:117]
	v_mfma_f32_16x16x32_bf16 v[102:105], v[174:177], v[234:237], v[102:105]
	v_mfma_f32_16x16x32_bf16 v[98:101], v[182:185], v[234:237], v[98:101]
	v_mfma_f32_16x16x32_bf16 v[68:71], v[174:177], v[242:245], v[68:71]
	v_mfma_f32_16x16x32_bf16 v[64:67], v[182:185], v[242:245], v[64:67]
	s_setprio 0
	s_setprio 1
	v_mfma_f32_16x16x32_bf16 v[142:145], v[186:189], v[202:205], v[142:145]
	v_mfma_f32_16x16x32_bf16 v[138:141], v[194:197], v[202:205], v[138:141]
	v_mfma_f32_16x16x32_bf16 v[126:129], v[186:189], v[210:213], v[126:129]
	v_mfma_f32_16x16x32_bf16 v[122:125], v[194:197], v[210:213], v[122:125]
	v_mfma_f32_16x16x32_bf16 v[110:113], v[186:189], v[230:233], v[110:113]
	v_mfma_f32_16x16x32_bf16 v[106:109], v[194:197], v[230:233], v[106:109]
	v_mfma_f32_16x16x32_bf16 v[76:79], v[186:189], v[238:241], v[76:79]
	v_mfma_f32_16x16x32_bf16 v[72:75], v[194:197], v[238:241], v[72:75]
	v_mfma_f32_16x16x32_bf16 v[142:145], v[190:193], v[206:209], v[142:145]
	v_mfma_f32_16x16x32_bf16 v[138:141], v[198:201], v[206:209], v[138:141]
	v_mfma_f32_16x16x32_bf16 v[126:129], v[190:193], v[226:229], v[126:129]
	v_mfma_f32_16x16x32_bf16 v[122:125], v[198:201], v[226:229], v[122:125]
	v_mfma_f32_16x16x32_bf16 v[110:113], v[190:193], v[234:237], v[110:113]
	v_mfma_f32_16x16x32_bf16 v[106:109], v[198:201], v[234:237], v[106:109]
	v_mfma_f32_16x16x32_bf16 v[76:79], v[190:193], v[242:245], v[76:79]
	v_mfma_f32_16x16x32_bf16 v[72:75], v[198:201], v[242:245], v[72:75]
	s_setprio 0
	s_barrier
; #define PG8_STAGE(bufoff, gbase, voff) do { _Pragma("unroll") for (int _i = 0; _i < 2; ++_i) \
;         __builtin_amdgcn_global_load_lds((const unsigned*)((const char*)(gbase) + (voff)[_i]), (LAS unsigned*)(lds + (bufoff) + ldsw + _i * 8192), 16, 0, 0); } while (0)
; #define PG8_LDA(dst, b, h) do { _Pragma("unroll") for (int m = 0; m < 4; ++m) _Pragma("unroll") for (int k = 0; k < 2; ++k) dst[m][k] = *(const LAS bf16x8*)(lds + PG8_SA(b, h) + aoff + m * 2048 + k * 1024); } while (0)
; #define PG8_MMA(ai, bj, At, Bt) do { __builtin_amdgcn_s_setprio(1); _Pragma("unroll") for (int m = 0; m < 4; ++m) _Pragma("unroll") for (int n = 0; n < 2; ++n) _Pragma("unroll") for (int k = 0; k < 2; ++k) \
;         acc[ai][bj][m][n] = __builtin_amdgcn_mfma_f32_16x16x32_bf16(Bt[n][k], At[m][k], acc[ai][bj][m][n], 0, 0, 0); __builtin_amdgcn_s_setprio(0); } while (0)
; #define PG8_WAIT_V(n) asm volatile("s_waitcnt vmcnt(" #n ")" ::: "memory")
; #define PG8_WAIT_L(n) asm volatile("s_waitcnt lgkmcnt(" #n ")" ::: "memory")
; #define PG8_BAR __builtin_amdgcn_s_barrier()
; #define PG8_SCHED __builtin_amdgcn_sched_barrier(0)
; template <class Epi>
; DI void gemm_phase(LAS unsigned char* lds, const Gemm g, const StaticOrder& S, const Epi& E) {
;     ...
;             PG8_LDA(At, 1, 1); PG8_STAGE(PG8_SB(1, 0), b3, voffB); PG8_STAGE(PG8_SB(1, 1), b3 + hstep, voffB); PG8_STAGE(PG8_SA(1, 0), a3, voffA);
;             PG8_WAIT_V(8); PG8_WAIT_L(0); PG8_BAR; PG8_MMA(1, 0, At, B0); PG8_MMA(1, 1, At, B1); PG8_BAR; PG8_SCHED;
;         }
;         if (wr == 0) PG8_BAR;
;     DI void operator()(AccRef acc, const Unit& u, int wr, int wc, int fr, int fq) const {
;     ...
;             for (int m = 0; m < 4; ++m) { const int row = row0 + ai * 128 + m * 16; bf16_t* rowp = O + (size_t)row * ldc + col0; const float rr = rs[row];
	s_add_i32 s20, s46, s26
	v_lshl_add_u64 v[160:161], v[160:161], 0, s[68:69]
	s_mov_b32 m0, s20
	ds_read_b128 v[202:205], v165 offset:49152
	ds_read_b128 v[206:209], v165 offset:50176
	ds_read_b128 v[210:213], v165 offset:51200
	ds_read_b128 v[226:229], v165 offset:52224
	ds_read_b128 v[230:233], v165 offset:53248
	ds_read_b128 v[234:237], v165 offset:54272
	ds_read_b128 v[238:241], v165 offset:55296
	ds_read_b128 v[242:245], v165 offset:56320
	global_load_lds_dwordx4 v[160:161], off
	s_add_i32 m0, s20, 0x2000
	s_add_u32 s16, s16, 0x80080
	v_lshl_add_u64 v[160:161], v[214:215], 0, s[68:69]
	s_addc_u32 s17, s17, 0
	s_add_i32 s20, s47, s26
	global_load_lds_dwordx4 v[160:161], off
	v_lshl_add_u64 v[160:161], s[16:17], 0, v[80:81]
	s_mov_b32 m0, s20
	s_nop 0
	global_load_lds_dwordx4 v[160:161], off
	v_lshl_add_u64 v[160:161], s[16:17], 0, v[146:147]
	s_add_i32 m0, s20, 0x2000
	s_nop 0
	global_load_lds_dwordx4 v[160:161], off
	v_lshl_add_u64 v[160:161], v[216:217], 0, s[68:69]
	s_mov_b32 m0, s31
	s_nop 0
	global_load_lds_dwordx4 v[160:161], off
	v_lshl_add_u64 v[160:161], v[218:219], 0, s[68:69]
	s_mov_b32 m0, s34
	s_nop 0
	global_load_lds_dwordx4 v[160:161], off
	s_waitcnt vmcnt(8)
	s_waitcnt lgkmcnt(0)
	s_barrier
	s_setprio 1
	s_waitcnt lgkmcnt(0)
	v_mfma_f32_16x16x32_bf16 v[52:55], v[156:159], v[202:205], v[52:55]
	v_mfma_f32_16x16x32_bf16 v[48:51], v[178:181], v[202:205], v[48:51]
	v_mfma_f32_16x16x32_bf16 v[36:39], v[156:159], v[210:213], v[36:39]
	v_mfma_f32_16x16x32_bf16 v[32:35], v[178:181], v[210:213], v[32:35]
	v_mfma_f32_16x16x32_bf16 v[20:23], v[156:159], v[230:233], v[20:23]
	v_mfma_f32_16x16x32_bf16 v[16:19], v[178:181], v[230:233], v[16:19]
	v_mfma_f32_16x16x32_bf16 v[4:7], v[156:159], v[238:241], v[4:7]
	v_mfma_f32_16x16x32_bf16 v[0:3], v[178:181], v[238:241], v[0:3]
	v_mfma_f32_16x16x32_bf16 v[52:55], v[174:177], v[206:209], v[52:55]
	v_mfma_f32_16x16x32_bf16 v[48:51], v[182:185], v[206:209], v[48:51]
	v_mfma_f32_16x16x32_bf16 v[36:39], v[174:177], v[226:229], v[36:39]
	v_mfma_f32_16x16x32_bf16 v[32:35], v[182:185], v[226:229], v[32:35]
	v_mfma_f32_16x16x32_bf16 v[20:23], v[174:177], v[234:237], v[20:23]
	v_mfma_f32_16x16x32_bf16 v[16:19], v[182:185], v[234:237], v[16:19]
	v_mfma_f32_16x16x32_bf16 v[4:7], v[174:177], v[242:245], v[4:7]
	v_mfma_f32_16x16x32_bf16 v[0:3], v[182:185], v[242:245], v[0:3]
	s_setprio 0
	s_setprio 1
	v_mfma_f32_16x16x32_bf16 v[60:63], v[186:189], v[202:205], v[60:63]
	v_mfma_f32_16x16x32_bf16 v[56:59], v[194:197], v[202:205], v[56:59]
	v_mfma_f32_16x16x32_bf16 v[44:47], v[186:189], v[210:213], v[44:47]
	v_mfma_f32_16x16x32_bf16 v[40:43], v[194:197], v[210:213], v[40:43]
	v_mfma_f32_16x16x32_bf16 v[28:31], v[186:189], v[230:233], v[28:31]
	v_mfma_f32_16x16x32_bf16 v[24:27], v[194:197], v[230:233], v[24:27]
	v_mfma_f32_16x16x32_bf16 v[12:15], v[186:189], v[238:241], v[12:15]
	v_mfma_f32_16x16x32_bf16 v[8:11], v[194:197], v[238:241], v[8:11]
	v_mfma_f32_16x16x32_bf16 v[60:63], v[190:193], v[206:209], v[60:63]
	v_mfma_f32_16x16x32_bf16 v[56:59], v[198:201], v[206:209], v[56:59]
	v_mfma_f32_16x16x32_bf16 v[44:47], v[190:193], v[226:229], v[44:47]
	v_mfma_f32_16x16x32_bf16 v[40:43], v[198:201], v[226:229], v[40:43]
	v_mfma_f32_16x16x32_bf16 v[28:31], v[190:193], v[234:237], v[28:31]
	v_mfma_f32_16x16x32_bf16 v[24:27], v[198:201], v[234:237], v[24:27]
	v_mfma_f32_16x16x32_bf16 v[12:15], v[190:193], v[242:245], v[12:15]
	v_mfma_f32_16x16x32_bf16 v[8:11], v[198:201], v[242:245], v[8:11]
	s_setprio 0
	s_barrier
	s_add_i32 s43, s43, 2
	s_add_u32 s18, s18, 0x100
	s_addc_u32 s19, s19, 0
	s_add_u32 s41, s41, 0x100
	s_addc_u32 s42, s42, 0
	s_cmp_gt_u32 s43, 29
	s_cbranch_scc0 .LBB0_701
	v_lshl_add_u32 v156, s38, 8, v163
	v_ashrrev_i32_e32 v157, 31, v156
	v_lshl_add_u64 v[160:161], v[156:157], 2, s[2:3]
	global_load_dword v178, v[160:161], off
	global_load_dword v196, v[160:161], off offset:64
	global_load_dword v197, v[160:161], off offset:128
	global_load_dword v198, v[160:161], off offset:192
	global_load_dword v199, v[160:161], off offset:512
	global_load_dword v200, v[160:161], off offset:576
	global_load_dword v201, v[160:161], off offset:640
	global_load_dword v202, v[160:161], off offset:704
	s_and_b64 vcc, exec, s[4:5]
	s_cbranch_vccz .LBB0_704
	s_barrier
; DI u32x4 pack8f(const float (&f)[8]) { u32x4 w; w.x = pk2(f[0], f[1]); w.y = pk2(f[2], f[3]); w.z = pk2(f[4], f[5]); w.w = pk2(f[6], f[7]); return w; }
; DI float siluf_(float x) { return x * sigmoidf_(x); }
;     DI void operator()(AccRef acc, const Unit& u, int wr, int wc, int fr, int fq) const {
;         const int row0 = u.pm * 256 + wr * 64 + fr, col0 = u.pn * 128 + wc * 32 + 8 * fq;
; #pragma unroll
;         for (int ai = 0; ai < 2; ++ai)
; #pragma unroll
;             for (int m = 0; m < 4; ++m) { const int row = row0 + ai * 128 + m * 16; bf16_t* rowp = O + (size_t)row * ldc + col0; const float rr = rs[row];
;                 float r[8];
; #pragma unroll
;                 for (int n = 0; n < 2; ++n)
; #pragma unroll
;                     for (int e = 0; e < 4; ++e) r[4 * n + e] = siluf_(acc[ai][0][m][n][e] * rr) * (acc[ai][1][m][n][e] * rr);
;                 *(u32x4*)rowp = pack8f(r); }
.LBB0_704:
	v_lshl_or_b32 v174, s36, 7, v164
	v_ashrrev_i32_e32 v175, 31, v174
	v_mov_b64_e32 v[158:159], s[88:89]
	v_mad_i64_i32 v[176:177], s[16:17], v156, s50, v[158:159]
	s_andn2_b64 vcc, exec, s[6:7]
	s_waitcnt vmcnt(0)
	v_pk_mul_f32 v[134:135], v[134:135], v[178:179] op_sel_hi:[1,0]
	s_nop 0
	v_mul_f32_e32 v157, 0xbfb8aa3b, v134
	v_exp_f32_e32 v157, v157
	v_pk_mul_f32 v[142:143], v[142:143], v[178:179] op_sel_hi:[1,0]
	v_pk_mul_f32 v[136:137], v[136:137], v[178:179] op_sel_hi:[1,0]
	v_pk_mul_f32 v[130:131], v[130:131], v[178:179] op_sel_hi:[1,0]
	v_add_f32_e32 v157, 1.0, v157
	v_rcp_f32_e32 v180, v157
	v_mul_f32_e32 v157, 0xbfb8aa3b, v135
	v_exp_f32_e32 v157, v157
	v_pk_mul_f32 v[138:139], v[138:139], v[178:179] op_sel_hi:[1,0]
	v_add_f32_e32 v157, 1.0, v157
	v_rcp_f32_e32 v181, v157
	s_nop 0
	v_pk_mul_f32 v[134:135], v[134:135], v[180:181]
	s_nop 0
	v_pk_mul_f32 v[134:135], v[142:143], v[134:135]
	v_mul_f32_e32 v142, 0xbfb8aa3b, v136
	v_mul_f32_e32 v143, 0xbfb8aa3b, v137
	v_exp_f32_e32 v142, v142
	v_exp_f32_e32 v143, v143
	v_add_f32_e32 v142, 1.0, v142
	v_add_f32_e32 v143, 1.0, v143
	v_rcp_f32_e32 v142, v142
	v_rcp_f32_e32 v143, v143
	s_nop 0
	v_pk_mul_f32 v[136:137], v[136:137], v[142:143]
	v_pk_mul_f32 v[142:143], v[144:145], v[178:179] op_sel_hi:[1,0]
	s_nop 0
	v_pk_mul_f32 v[136:137], v[142:143], v[136:137]
	v_mul_f32_e32 v142, 0xbfb8aa3b, v130
	v_mul_f32_e32 v143, 0xbfb8aa3b, v131
	v_exp_f32_e32 v142, v142
	v_exp_f32_e32 v143, v143
	v_add_f32_e32 v142, 1.0, v142
	v_add_f32_e32 v143, 1.0, v143
	v_rcp_f32_e32 v142, v142
	v_rcp_f32_e32 v143, v143
	s_nop 0
	v_pk_mul_f32 v[130:131], v[130:131], v[142:143]
	s_nop 0
	v_pk_mul_f32 v[138:139], v[138:139], v[130:131]
	v_pk_mul_f32 v[130:131], v[132:133], v[178:179] op_sel_hi:[1,0]
	s_nop 0
	v_mul_f32_e32 v132, 0xbfb8aa3b, v130
	v_mul_f32_e32 v133, 0xbfb8aa3b, v131
	v_exp_f32_e32 v132, v132
	v_exp_f32_e32 v133, v133
	v_add_f32_e32 v132, 1.0, v132
	v_add_f32_e32 v133, 1.0, v133
	v_rcp_f32_e32 v132, v132
	v_rcp_f32_e32 v133, v133
	s_nop 0
	v_pk_mul_f32 v[130:131], v[130:131], v[132:133]
	v_pk_mul_f32 v[132:133], v[140:141], v[178:179] op_sel_hi:[1,0]
	s_nop 0
	v_pk_mul_f32 v[140:141], v[132:133], v[130:131]
	v_lshlrev_b64 v[130:131], 1, v[174:175]
	v_lshl_add_u64 v[142:143], v[176:177], 0, v[130:131]
	v_cvt_pk_bf16_f32 v132, v134, v135
	v_cvt_pk_bf16_f32 v133, v136, v137
	v_cvt_pk_bf16_f32 v134, v138, v139
	v_cvt_pk_bf16_f32 v135, v140, v141
	global_store_dwordx4 v[142:143], v[132:135], off
	s_nop 1
	v_or_b32_e32 v134, 16, v156
	v_ashrrev_i32_e32 v135, 31, v134
	v_mad_i64_i32 v[132:133], s[16:17], v134, s50, v[158:159]
	v_lshl_add_u64 v[134:135], v[134:135], 2, s[2:3]
	v_mov_b32_e32 v134, v196
	v_pk_mul_f32 v[118:119], v[118:119], v[134:135] op_sel_hi:[1,0]
	s_nop 0
	v_mul_f32_e32 v135, 0xbfb8aa3b, v118
	v_exp_f32_e32 v135, v135
	s_nop 0
	v_add_f32_e32 v135, 1.0, v135
	v_rcp_f32_e32 v136, v135
	v_mul_f32_e32 v135, 0xbfb8aa3b, v119
	v_exp_f32_e32 v135, v135
	s_nop 0
	v_add_f32_e32 v135, 1.0, v135
	v_rcp_f32_e32 v137, v135
	v_pk_mul_f32 v[126:127], v[126:127], v[134:135] op_sel_hi:[1,0]
	v_pk_mul_f32 v[120:121], v[120:121], v[134:135] op_sel_hi:[1,0]
	v_pk_mul_f32 v[114:115], v[114:115], v[134:135] op_sel_hi:[1,0]
	v_pk_mul_f32 v[118:119], v[118:119], v[136:137]
	v_pk_mul_f32 v[122:123], v[122:123], v[134:135] op_sel_hi:[1,0]
	v_pk_mul_f32 v[118:119], v[126:127], v[118:119]
	v_mul_f32_e32 v126, 0xbfb8aa3b, v120
	v_mul_f32_e32 v127, 0xbfb8aa3b, v121
	v_exp_f32_e32 v126, v126
	v_exp_f32_e32 v127, v127
	v_add_f32_e32 v126, 1.0, v126
	v_add_f32_e32 v127, 1.0, v127
	v_rcp_f32_e32 v126, v126
	v_rcp_f32_e32 v127, v127
	s_nop 0
	v_pk_mul_f32 v[120:121], v[120:121], v[126:127]
	v_pk_mul_f32 v[126:127], v[128:129], v[134:135] op_sel_hi:[1,0]
	s_nop 0
	v_pk_mul_f32 v[120:121], v[126:127], v[120:121]
	v_mul_f32_e32 v126, 0xbfb8aa3b, v114
	v_mul_f32_e32 v127, 0xbfb8aa3b, v115
	v_exp_f32_e32 v126, v126
	v_exp_f32_e32 v127, v127
	v_add_f32_e32 v126, 1.0, v126
	v_add_f32_e32 v127, 1.0, v127
	v_rcp_f32_e32 v126, v126
	v_rcp_f32_e32 v127, v127
	s_nop 0
	v_pk_mul_f32 v[114:115], v[114:115], v[126:127]
	s_nop 0
	v_pk_mul_f32 v[122:123], v[122:123], v[114:115]
	v_pk_mul_f32 v[114:115], v[116:117], v[134:135] op_sel_hi:[1,0]
	v_lshl_add_u64 v[126:127], v[132:133], 0, v[130:131]
	v_mul_f32_e32 v116, 0xbfb8aa3b, v114
	v_mul_f32_e32 v117, 0xbfb8aa3b, v115
	v_exp_f32_e32 v116, v116
	v_exp_f32_e32 v117, v117
	v_add_f32_e32 v116, 1.0, v116
	v_add_f32_e32 v117, 1.0, v117
	v_rcp_f32_e32 v116, v116
	v_rcp_f32_e32 v117, v117
	s_nop 0
	v_pk_mul_f32 v[114:115], v[114:115], v[116:117]
	v_pk_mul_f32 v[116:117], v[124:125], v[134:135] op_sel_hi:[1,0]
	s_nop 0
	v_pk_mul_f32 v[124:125], v[116:117], v[114:115]
	v_cvt_pk_bf16_f32 v114, v118, v119
	v_cvt_pk_bf16_f32 v115, v120, v121
	v_cvt_pk_bf16_f32 v116, v122, v123
	v_cvt_pk_bf16_f32 v117, v124, v125
	global_store_dwordx4 v[126:127], v[114:117], off
	s_nop 1
	v_or_b32_e32 v116, 32, v156
	v_ashrrev_i32_e32 v117, 31, v116
	v_mad_i64_i32 v[114:115], s[16:17], v116, s50, v[158:159]
	v_lshl_add_u64 v[116:117], v[116:117], 2, s[2:3]
	v_mov_b32_e32 v116, v197
	v_pk_mul_f32 v[102:103], v[102:103], v[116:117] op_sel_hi:[1,0]
	s_nop 0
	v_mul_f32_e32 v117, 0xbfb8aa3b, v102
	v_exp_f32_e32 v117, v117
	s_nop 0
	v_add_f32_e32 v117, 1.0, v117
	v_rcp_f32_e32 v118, v117
	v_mul_f32_e32 v117, 0xbfb8aa3b, v103
	v_exp_f32_e32 v117, v117
	s_nop 0
	v_add_f32_e32 v117, 1.0, v117
	v_rcp_f32_e32 v119, v117
	v_pk_mul_f32 v[110:111], v[110:111], v[116:117] op_sel_hi:[1,0]
	v_pk_mul_f32 v[104:105], v[104:105], v[116:117] op_sel_hi:[1,0]
	v_pk_mul_f32 v[98:99], v[98:99], v[116:117] op_sel_hi:[1,0]
; DI u32x4 pack8f(const float (&f)[8]) { u32x4 w; w.x = pk2(f[0], f[1]); w.y = pk2(f[2], f[3]); w.z = pk2(f[4], f[5]); w.w = pk2(f[6], f[7]); return w; }
; DI float siluf_(float x) { return x * sigmoidf_(x); }
;     DI void operator()(AccRef acc, const Unit& u, int wr, int wc, int fr, int fq) const {
;     ...
;             for (int m = 0; m < 4; ++m) { const int row = row0 + ai * 128 + m * 16; bf16_t* rowp = O + (size_t)row * ldc + col0; const float rr = rs[row];
;                 float r[8];
; #pragma unroll
;                 for (int n = 0; n < 2; ++n)
; #pragma unroll
;                     for (int e = 0; e < 4; ++e) r[4 * n + e] = siluf_(acc[ai][0][m][n][e] * rr) * (acc[ai][1][m][n][e] * rr);
;                 *(u32x4*)rowp = pack8f(r); }
	v_pk_mul_f32 v[102:103], v[102:103], v[118:119]
	v_pk_mul_f32 v[106:107], v[106:107], v[116:117] op_sel_hi:[1,0]
	v_pk_mul_f32 v[102:103], v[110:111], v[102:103]
	v_mul_f32_e32 v110, 0xbfb8aa3b, v104
	v_mul_f32_e32 v111, 0xbfb8aa3b, v105
	v_exp_f32_e32 v110, v110
	v_exp_f32_e32 v111, v111
	v_add_f32_e32 v110, 1.0, v110
	v_add_f32_e32 v111, 1.0, v111
	v_rcp_f32_e32 v110, v110
	v_rcp_f32_e32 v111, v111
	s_nop 0
	v_pk_mul_f32 v[104:105], v[104:105], v[110:111]
	v_pk_mul_f32 v[110:111], v[112:113], v[116:117] op_sel_hi:[1,0]
	s_nop 0
	v_pk_mul_f32 v[104:105], v[110:111], v[104:105]
	v_mul_f32_e32 v110, 0xbfb8aa3b, v98
	v_mul_f32_e32 v111, 0xbfb8aa3b, v99
	v_exp_f32_e32 v110, v110
	v_exp_f32_e32 v111, v111
	v_add_f32_e32 v110, 1.0, v110
	v_add_f32_e32 v111, 1.0, v111
	v_rcp_f32_e32 v110, v110
	v_rcp_f32_e32 v111, v111
	s_nop 0
	v_pk_mul_f32 v[98:99], v[98:99], v[110:111]
	s_nop 0
	v_pk_mul_f32 v[106:107], v[106:107], v[98:99]
	v_pk_mul_f32 v[98:99], v[100:101], v[116:117] op_sel_hi:[1,0]
	v_lshl_add_u64 v[110:111], v[114:115], 0, v[130:131]
	v_mul_f32_e32 v100, 0xbfb8aa3b, v98
	v_mul_f32_e32 v101, 0xbfb8aa3b, v99
	v_exp_f32_e32 v100, v100
	v_exp_f32_e32 v101, v101
	v_add_f32_e32 v100, 1.0, v100
	v_add_f32_e32 v101, 1.0, v101
	v_rcp_f32_e32 v100, v100
	v_rcp_f32_e32 v101, v101
	s_nop 0
	v_pk_mul_f32 v[98:99], v[98:99], v[100:101]
	v_pk_mul_f32 v[100:101], v[108:109], v[116:117] op_sel_hi:[1,0]
	s_nop 0
	v_pk_mul_f32 v[108:109], v[100:101], v[98:99]
	v_cvt_pk_bf16_f32 v98, v102, v103
	v_cvt_pk_bf16_f32 v99, v104, v105
	v_cvt_pk_bf16_f32 v100, v106, v107
	v_cvt_pk_bf16_f32 v101, v108, v109
	global_store_dwordx4 v[110:111], v[98:101], off
	s_nop 1
	v_or_b32_e32 v100, 48, v156
	v_ashrrev_i32_e32 v101, 31, v100
	v_mad_i64_i32 v[98:99], s[16:17], v100, s50, v[158:159]
	v_lshl_add_u64 v[100:101], v[100:101], 2, s[2:3]
	v_mov_b32_e32 v100, v198
	v_pk_mul_f32 v[68:69], v[68:69], v[100:101] op_sel_hi:[1,0]
	s_nop 0
	v_mul_f32_e32 v101, 0xbfb8aa3b, v68
	v_exp_f32_e32 v101, v101
	s_nop 0
	v_add_f32_e32 v101, 1.0, v101
	v_rcp_f32_e32 v102, v101
	v_mul_f32_e32 v101, 0xbfb8aa3b, v69
	v_exp_f32_e32 v101, v101
	s_nop 0
	v_add_f32_e32 v101, 1.0, v101
	v_rcp_f32_e32 v103, v101
	v_pk_mul_f32 v[76:77], v[76:77], v[100:101] op_sel_hi:[1,0]
	v_pk_mul_f32 v[70:71], v[70:71], v[100:101] op_sel_hi:[1,0]
	v_pk_mul_f32 v[64:65], v[64:65], v[100:101] op_sel_hi:[1,0]
	v_pk_mul_f32 v[68:69], v[68:69], v[102:103]
	v_pk_mul_f32 v[72:73], v[72:73], v[100:101] op_sel_hi:[1,0]
	v_pk_mul_f32 v[68:69], v[76:77], v[68:69]
	v_mul_f32_e32 v76, 0xbfb8aa3b, v70
	v_mul_f32_e32 v77, 0xbfb8aa3b, v71
	v_exp_f32_e32 v76, v76
	v_exp_f32_e32 v77, v77
	v_pk_mul_f32 v[66:67], v[66:67], v[100:101] op_sel_hi:[1,0]
	v_cvt_pk_bf16_f32 v68, v68, v69
	v_add_f32_e32 v76, 1.0, v76
	v_add_f32_e32 v77, 1.0, v77
	v_rcp_f32_e32 v76, v76
	v_rcp_f32_e32 v77, v77
	s_nop 0
	v_pk_mul_f32 v[70:71], v[70:71], v[76:77]
	v_pk_mul_f32 v[76:77], v[78:79], v[100:101] op_sel_hi:[1,0]
	s_nop 0
	v_pk_mul_f32 v[70:71], v[76:77], v[70:71]
	v_mul_f32_e32 v76, 0xbfb8aa3b, v64
	v_mul_f32_e32 v77, 0xbfb8aa3b, v65
	v_exp_f32_e32 v76, v76
	v_exp_f32_e32 v77, v77
	v_cvt_pk_bf16_f32 v69, v70, v71
	v_add_f32_e32 v76, 1.0, v76
	v_add_f32_e32 v77, 1.0, v77
	v_rcp_f32_e32 v76, v76
	v_rcp_f32_e32 v77, v77
	s_nop 0
	v_pk_mul_f32 v[64:65], v[64:65], v[76:77]
	s_nop 0
	v_pk_mul_f32 v[64:65], v[72:73], v[64:65]
	v_mul_f32_e32 v72, 0xbfb8aa3b, v66
	v_mul_f32_e32 v73, 0xbfb8aa3b, v67
	v_exp_f32_e32 v72, v72
	v_exp_f32_e32 v73, v73
	v_cvt_pk_bf16_f32 v70, v64, v65
	v_add_u32_e32 v64, 0x80, v156
	v_add_f32_e32 v72, 1.0, v72
	v_add_f32_e32 v73, 1.0, v73
	v_rcp_f32_e32 v72, v72
	v_rcp_f32_e32 v73, v73
	v_mad_i64_i32 v[64:65], s[16:17], v64, s50, v[158:159]
	v_pk_mul_f32 v[66:67], v[66:67], v[72:73]
	v_pk_mul_f32 v[72:73], v[74:75], v[100:101] op_sel_hi:[1,0]
	s_nop 0
	v_pk_mul_f32 v[66:67], v[72:73], v[66:67]
	v_lshl_add_u64 v[72:73], v[98:99], 0, v[130:131]
	v_cvt_pk_bf16_f32 v71, v66, v67
	global_store_dwordx4 v[72:73], v[68:71], off
	v_mov_b32_e32 v66, v199
	v_pk_mul_f32 v[52:53], v[52:53], v[66:67] op_sel_hi:[1,0]
	s_nop 0
	v_mul_f32_e32 v67, 0xbfb8aa3b, v52
	v_exp_f32_e32 v67, v67
	s_nop 0
	v_add_f32_e32 v67, 1.0, v67
	v_rcp_f32_e32 v68, v67
	v_mul_f32_e32 v67, 0xbfb8aa3b, v53
	v_exp_f32_e32 v67, v67
	s_nop 0
	v_add_f32_e32 v67, 1.0, v67
	v_rcp_f32_e32 v69, v67
	v_pk_mul_f32 v[60:61], v[60:61], v[66:67] op_sel_hi:[1,0]
	v_pk_mul_f32 v[54:55], v[54:55], v[66:67] op_sel_hi:[1,0]
	v_pk_mul_f32 v[48:49], v[48:49], v[66:67] op_sel_hi:[1,0]
	v_pk_mul_f32 v[52:53], v[52:53], v[68:69]
	v_pk_mul_f32 v[56:57], v[56:57], v[66:67] op_sel_hi:[1,0]
	v_pk_mul_f32 v[52:53], v[60:61], v[52:53]
	v_mul_f32_e32 v60, 0xbfb8aa3b, v54
	v_mul_f32_e32 v61, 0xbfb8aa3b, v55
	v_exp_f32_e32 v60, v60
	v_exp_f32_e32 v61, v61
	v_pk_mul_f32 v[50:51], v[50:51], v[66:67] op_sel_hi:[1,0]
	v_cvt_pk_bf16_f32 v52, v52, v53
	v_add_f32_e32 v60, 1.0, v60
	v_add_f32_e32 v61, 1.0, v61
	v_rcp_f32_e32 v60, v60
	v_rcp_f32_e32 v61, v61
	s_nop 0
	v_pk_mul_f32 v[54:55], v[54:55], v[60:61]
	v_pk_mul_f32 v[60:61], v[62:63], v[66:67] op_sel_hi:[1,0]
	s_nop 0
	v_pk_mul_f32 v[54:55], v[60:61], v[54:55]
	v_mul_f32_e32 v60, 0xbfb8aa3b, v48
	v_mul_f32_e32 v61, 0xbfb8aa3b, v49
	v_exp_f32_e32 v60, v60
	v_exp_f32_e32 v61, v61
	v_cvt_pk_bf16_f32 v53, v54, v55
	v_add_f32_e32 v60, 1.0, v60
	v_add_f32_e32 v61, 1.0, v61
	v_rcp_f32_e32 v60, v60
	v_rcp_f32_e32 v61, v61
	s_nop 0
	v_pk_mul_f32 v[48:49], v[48:49], v[60:61]
	s_nop 0
	v_pk_mul_f32 v[48:49], v[56:57], v[48:49]
	v_mul_f32_e32 v56, 0xbfb8aa3b, v50
	v_mul_f32_e32 v57, 0xbfb8aa3b, v51
	v_exp_f32_e32 v56, v56
	v_exp_f32_e32 v57, v57
; DI u32x4 pack8f(const float (&f)[8]) { u32x4 w; w.x = pk2(f[0], f[1]); w.y = pk2(f[2], f[3]); w.z = pk2(f[4], f[5]); w.w = pk2(f[6], f[7]); return w; }
; DI float siluf_(float x) { return x * sigmoidf_(x); }
;     DI void operator()(AccRef acc, const Unit& u, int wr, int wc, int fr, int fq) const {
;     ...
;             for (int m = 0; m < 4; ++m) { const int row = row0 + ai * 128 + m * 16; bf16_t* rowp = O + (size_t)row * ldc + col0; const float rr = rs[row];
;                 float r[8];
; #pragma unroll
;                 for (int n = 0; n < 2; ++n)
; #pragma unroll
;                     for (int e = 0; e < 4; ++e) r[4 * n + e] = siluf_(acc[ai][0][m][n][e] * rr) * (acc[ai][1][m][n][e] * rr);
;                 *(u32x4*)rowp = pack8f(r); }
	v_cvt_pk_bf16_f32 v54, v48, v49
	v_add_u32_e32 v48, 0x90, v156
	v_add_f32_e32 v56, 1.0, v56
	v_add_f32_e32 v57, 1.0, v57
	v_rcp_f32_e32 v56, v56
	v_rcp_f32_e32 v57, v57
	v_mad_i64_i32 v[48:49], s[16:17], v48, s50, v[158:159]
	v_pk_mul_f32 v[50:51], v[50:51], v[56:57]
	v_pk_mul_f32 v[56:57], v[58:59], v[66:67] op_sel_hi:[1,0]
	s_nop 0
	v_pk_mul_f32 v[50:51], v[56:57], v[50:51]
	v_lshl_add_u64 v[56:57], v[64:65], 0, v[130:131]
	v_cvt_pk_bf16_f32 v55, v50, v51
	global_store_dwordx4 v[56:57], v[52:55], off
	v_mov_b32_e32 v50, v200
	v_pk_mul_f32 v[36:37], v[36:37], v[50:51] op_sel_hi:[1,0]
	s_nop 0
	v_mul_f32_e32 v51, 0xbfb8aa3b, v36
	v_exp_f32_e32 v51, v51
	s_nop 0
	v_add_f32_e32 v51, 1.0, v51
	v_rcp_f32_e32 v52, v51
	v_mul_f32_e32 v51, 0xbfb8aa3b, v37
	v_exp_f32_e32 v51, v51
	s_nop 0
	v_add_f32_e32 v51, 1.0, v51
	v_rcp_f32_e32 v53, v51
	v_pk_mul_f32 v[44:45], v[44:45], v[50:51] op_sel_hi:[1,0]
	v_pk_mul_f32 v[38:39], v[38:39], v[50:51] op_sel_hi:[1,0]
	v_pk_mul_f32 v[32:33], v[32:33], v[50:51] op_sel_hi:[1,0]
	v_pk_mul_f32 v[36:37], v[36:37], v[52:53]
	v_pk_mul_f32 v[40:41], v[40:41], v[50:51] op_sel_hi:[1,0]
	v_pk_mul_f32 v[36:37], v[44:45], v[36:37]
	v_mul_f32_e32 v44, 0xbfb8aa3b, v38
	v_mul_f32_e32 v45, 0xbfb8aa3b, v39
	v_exp_f32_e32 v44, v44
	v_exp_f32_e32 v45, v45
	v_pk_mul_f32 v[34:35], v[34:35], v[50:51] op_sel_hi:[1,0]
	v_cvt_pk_bf16_f32 v36, v36, v37
	v_add_f32_e32 v44, 1.0, v44
	v_add_f32_e32 v45, 1.0, v45
	v_rcp_f32_e32 v44, v44
	v_rcp_f32_e32 v45, v45
	s_nop 0
	v_pk_mul_f32 v[38:39], v[38:39], v[44:45]
	v_pk_mul_f32 v[44:45], v[46:47], v[50:51] op_sel_hi:[1,0]
	s_nop 0
	v_pk_mul_f32 v[38:39], v[44:45], v[38:39]
	v_mul_f32_e32 v44, 0xbfb8aa3b, v32
	v_mul_f32_e32 v45, 0xbfb8aa3b, v33
	v_exp_f32_e32 v44, v44
	v_exp_f32_e32 v45, v45
	v_cvt_pk_bf16_f32 v37, v38, v39
	v_add_f32_e32 v44, 1.0, v44
	v_add_f32_e32 v45, 1.0, v45
	v_rcp_f32_e32 v44, v44
	v_rcp_f32_e32 v45, v45
	s_nop 0
	v_pk_mul_f32 v[32:33], v[32:33], v[44:45]
	s_nop 0
	v_pk_mul_f32 v[32:33], v[40:41], v[32:33]
	v_mul_f32_e32 v40, 0xbfb8aa3b, v34
	v_mul_f32_e32 v41, 0xbfb8aa3b, v35
	v_exp_f32_e32 v40, v40
	v_exp_f32_e32 v41, v41
	v_cvt_pk_bf16_f32 v38, v32, v33
	v_add_u32_e32 v32, 0xa0, v156
	v_add_f32_e32 v40, 1.0, v40
	v_add_f32_e32 v41, 1.0, v41
	v_rcp_f32_e32 v40, v40
	v_rcp_f32_e32 v41, v41
	v_mad_i64_i32 v[32:33], s[16:17], v32, s50, v[158:159]
	v_pk_mul_f32 v[34:35], v[34:35], v[40:41]
	v_pk_mul_f32 v[40:41], v[42:43], v[50:51] op_sel_hi:[1,0]
	s_nop 0
	v_pk_mul_f32 v[34:35], v[40:41], v[34:35]
	v_lshl_add_u64 v[40:41], v[48:49], 0, v[130:131]
	v_cvt_pk_bf16_f32 v39, v34, v35
	global_store_dwordx4 v[40:41], v[36:39], off
	v_mov_b32_e32 v34, v201
	v_pk_mul_f32 v[20:21], v[20:21], v[34:35] op_sel_hi:[1,0]
	s_nop 0
	v_mul_f32_e32 v35, 0xbfb8aa3b, v20
	v_exp_f32_e32 v35, v35
	s_nop 0
	v_add_f32_e32 v35, 1.0, v35
	v_rcp_f32_e32 v36, v35
	v_mul_f32_e32 v35, 0xbfb8aa3b, v21
	v_exp_f32_e32 v35, v35
	s_nop 0
	v_add_f32_e32 v35, 1.0, v35
	v_rcp_f32_e32 v37, v35
	v_pk_mul_f32 v[28:29], v[28:29], v[34:35] op_sel_hi:[1,0]
	v_pk_mul_f32 v[22:23], v[22:23], v[34:35] op_sel_hi:[1,0]
	v_pk_mul_f32 v[16:17], v[16:17], v[34:35] op_sel_hi:[1,0]
	v_pk_mul_f32 v[20:21], v[20:21], v[36:37]
	v_pk_mul_f32 v[24:25], v[24:25], v[34:35] op_sel_hi:[1,0]
	v_pk_mul_f32 v[20:21], v[28:29], v[20:21]
	v_mul_f32_e32 v28, 0xbfb8aa3b, v22
	v_mul_f32_e32 v29, 0xbfb8aa3b, v23
	v_exp_f32_e32 v28, v28
	v_exp_f32_e32 v29, v29
	v_pk_mul_f32 v[18:19], v[18:19], v[34:35] op_sel_hi:[1,0]
	v_cvt_pk_bf16_f32 v20, v20, v21
	v_add_f32_e32 v28, 1.0, v28
	v_add_f32_e32 v29, 1.0, v29
	v_rcp_f32_e32 v28, v28
	v_rcp_f32_e32 v29, v29
	s_nop 0
	v_pk_mul_f32 v[22:23], v[22:23], v[28:29]
	v_pk_mul_f32 v[28:29], v[30:31], v[34:35] op_sel_hi:[1,0]
	s_nop 0
	v_pk_mul_f32 v[22:23], v[28:29], v[22:23]
	v_mul_f32_e32 v28, 0xbfb8aa3b, v16
	v_mul_f32_e32 v29, 0xbfb8aa3b, v17
	v_exp_f32_e32 v28, v28
	v_exp_f32_e32 v29, v29
	v_cvt_pk_bf16_f32 v21, v22, v23
	v_add_f32_e32 v28, 1.0, v28
	v_add_f32_e32 v29, 1.0, v29
	v_rcp_f32_e32 v28, v28
	v_rcp_f32_e32 v29, v29
	s_nop 0
	v_pk_mul_f32 v[16:17], v[16:17], v[28:29]
	s_nop 0
	v_pk_mul_f32 v[16:17], v[24:25], v[16:17]
	v_mul_f32_e32 v24, 0xbfb8aa3b, v18
	v_mul_f32_e32 v25, 0xbfb8aa3b, v19
	v_exp_f32_e32 v24, v24
	v_exp_f32_e32 v25, v25
	v_cvt_pk_bf16_f32 v22, v16, v17
	v_add_u32_e32 v16, 0xb0, v156
	v_add_f32_e32 v24, 1.0, v24
	v_add_f32_e32 v25, 1.0, v25
	v_rcp_f32_e32 v24, v24
	v_rcp_f32_e32 v25, v25
	v_mad_i64_i32 v[16:17], s[16:17], v16, s50, v[158:159]
	s_mov_b64 s[16:17], -1
	v_pk_mul_f32 v[18:19], v[18:19], v[24:25]
	v_pk_mul_f32 v[24:25], v[26:27], v[34:35] op_sel_hi:[1,0]
	s_nop 0
	v_pk_mul_f32 v[18:19], v[24:25], v[18:19]
	v_lshl_add_u64 v[24:25], v[32:33], 0, v[130:131]
	v_cvt_pk_bf16_f32 v23, v18, v19
	global_store_dwordx4 v[24:25], v[20:23], off
	v_mov_b32_e32 v18, v202
	v_pk_mul_f32 v[4:5], v[4:5], v[18:19] op_sel_hi:[1,0]
	s_nop 0
	v_mul_f32_e32 v19, 0xbfb8aa3b, v4
	v_exp_f32_e32 v19, v19
	s_nop 0
	v_add_f32_e32 v19, 1.0, v19
	v_rcp_f32_e32 v20, v19
	v_mul_f32_e32 v19, 0xbfb8aa3b, v5
	v_exp_f32_e32 v19, v19
	s_nop 0
	v_add_f32_e32 v19, 1.0, v19
	v_rcp_f32_e32 v21, v19
	v_pk_mul_f32 v[12:13], v[12:13], v[18:19] op_sel_hi:[1,0]
	v_pk_mul_f32 v[6:7], v[6:7], v[18:19] op_sel_hi:[1,0]
	v_pk_mul_f32 v[0:1], v[0:1], v[18:19] op_sel_hi:[1,0]
	v_pk_mul_f32 v[4:5], v[4:5], v[20:21]
	v_pk_mul_f32 v[8:9], v[8:9], v[18:19] op_sel_hi:[1,0]
	v_pk_mul_f32 v[4:5], v[12:13], v[4:5]
	v_mul_f32_e32 v12, 0xbfb8aa3b, v6
	v_mul_f32_e32 v13, 0xbfb8aa3b, v7
	v_exp_f32_e32 v12, v12
	v_exp_f32_e32 v13, v13
	v_add_f32_e32 v12, 1.0, v12
	v_add_f32_e32 v13, 1.0, v13
	v_rcp_f32_e32 v12, v12
	v_rcp_f32_e32 v13, v13
	s_nop 0
	v_pk_mul_f32 v[6:7], v[6:7], v[12:13]
	v_pk_mul_f32 v[12:13], v[14:15], v[18:19] op_sel_hi:[1,0]
	s_nop 0
	v_pk_mul_f32 v[6:7], v[12:13], v[6:7]
	v_mul_f32_e32 v12, 0xbfb8aa3b, v0
	v_mul_f32_e32 v13, 0xbfb8aa3b, v1
	v_exp_f32_e32 v12, v12
	v_exp_f32_e32 v13, v13
	v_add_f32_e32 v12, 1.0, v12
	v_add_f32_e32 v13, 1.0, v13
	v_rcp_f32_e32 v12, v12
	v_rcp_f32_e32 v13, v13
	s_nop 0
	v_pk_mul_f32 v[0:1], v[0:1], v[12:13]
	s_nop 0
	v_pk_mul_f32 v[8:9], v[8:9], v[0:1]
	v_pk_mul_f32 v[0:1], v[2:3], v[18:19] op_sel_hi:[1,0]
	v_lshl_add_u64 v[12:13], v[16:17], 0, v[130:131]
	v_mul_f32_e32 v2, 0xbfb8aa3b, v0
	v_mul_f32_e32 v3, 0xbfb8aa3b, v1
	v_exp_f32_e32 v2, v2
	v_exp_f32_e32 v3, v3
	v_add_f32_e32 v2, 1.0, v2
	v_add_f32_e32 v3, 1.0, v3
	v_rcp_f32_e32 v2, v2
	v_rcp_f32_e32 v3, v3
	s_nop 0
	v_pk_mul_f32 v[0:1], v[0:1], v[2:3]
	v_pk_mul_f32 v[2:3], v[10:11], v[18:19] op_sel_hi:[1,0]
	s_nop 0
	v_pk_mul_f32 v[10:11], v[2:3], v[0:1]
	v_cvt_pk_bf16_f32 v0, v4, v5
	v_cvt_pk_bf16_f32 v1, v6, v7
	v_cvt_pk_bf16_f32 v2, v8, v9
	v_cvt_pk_bf16_f32 v3, v10, v11
	global_store_dwordx4 v[12:13], v[0:3], off
	s_cbranch_vccnz .LBB0_697
; #define PG8_BAR __builtin_amdgcn_s_barrier()
; template <class Epi>
; DI void gemm_phase(LAS unsigned char* lds, const Gemm g, const StaticOrder& S, const Epi& E) {
;     ...
; #pragma unroll
;         for (int a = 0; a < 2; ++a)
; #pragma unroll
;             for (int b = 0; b < 2; ++b)
; #pragma unroll
;                 for (int m = 0; m < 4; ++m)
; #pragma unroll
;                     for (int n = 0; n < 2; ++n) { float zz = 0.f; asm volatile("" : "+v"(zz)); acc[a][b][m][n] = (f32x4){zz, zz, zz, zz}; }
;         cur = nxt; cA = nA; cB = nB; ++ui;
;         if (wr == 1) PG8_BAR;
	v_mov_b32_e32 v134, 0
	v_mov_b32_e32 v130, 0
	v_mov_b32_e32 v118, 0
	v_mov_b32_e32 v114, 0
	v_mov_b32_e32 v102, 0
	v_mov_b32_e32 v98, 0
	v_mov_b32_e32 v68, 0
	v_mov_b32_e32 v64, 0
	v_mov_b32_e32 v142, 0
	v_mov_b32_e32 v138, 0
	v_mov_b32_e32 v126, 0
	v_mov_b32_e32 v122, 0
	v_mov_b32_e32 v110, 0
	v_mov_b32_e32 v106, 0
	v_mov_b32_e32 v76, 0
	v_mov_b32_e32 v72, 0
	v_mov_b32_e32 v52, 0
	v_mov_b32_e32 v48, 0
	v_mov_b32_e32 v36, 0
	v_mov_b32_e32 v32, 0
	v_mov_b32_e32 v20, 0
	v_mov_b32_e32 v16, 0
	v_mov_b32_e32 v4, 0
	v_mov_b32_e32 v0, 0
	v_mov_b32_e32 v60, 0
	v_mov_b32_e32 v56, 0
	v_mov_b32_e32 v44, 0
	v_mov_b32_e32 v40, 0
	v_mov_b32_e32 v28, 0
	v_mov_b32_e32 v24, 0
	v_mov_b32_e32 v12, 0
	v_mov_b32_e32 v8, 0
	s_andn2_b64 vcc, exec, s[0:1]
	s_cbranch_vccnz .LBB0_696
	s_barrier
	s_branch .LBB0_696
